# v82 + layer-0 PLE gate/proj weight conversion moved from the phase-3 staggered slot to the dedicated WGs of phase 7
# baseline (speedup 1.0000x reference)
; #define LAS __attribute__((address_space(3)))
; __device__ __forceinline__ unsigned cvt_pk_bf16(float lo, float hi) { unsigned r; asm volatile("v_cvt_pk_bf16_f32 %0, %1, %2" : "=v"(r) : "v"(lo), "v"(hi)); return r; }
; __device__ __forceinline__ void xpose_item(const float* src, int ld, bf16_t* dst, int K, int k0, LAS float* scr, int lane, const float* gk) {
;     if (src) {
; #pragma unroll 8
;         for (int i = 0; i < 32; ++i) { const int kk = 2 * i + (lane >> 5); scr[kk * 33 + (lane & 31)] = __builtin_nontemporal_load(src + (size_t)(k0 + kk) * ld + (lane & 31)); }
;     } else {
; #pragma unroll 8
;         for (int i = 0; i < 32; ++i) { const int kk = 2 * i + (lane >> 5); scr[kk * 33 + (lane & 31)] = 0.f; }
;     }
;     const int c = lane & 7;
;     f32x4 g0 = (f32x4){1.f, 1.f, 1.f, 1.f}, g1 = g0;
;     if (gk) { g0 = *(const f32x4*)(gk + k0 + 8 * c); g1 = *(const f32x4*)(gk + k0 + 8 * c + 4); }
;     asm volatile("s_waitcnt lgkmcnt(0)" ::: "memory");
; #pragma unroll
;     for (int j = 0; j < 4; ++j) { const int n = (lane >> 3) + 8 * j; const LAS float* s = scr + (8 * c) * 33 + n;
;         u32x4 o; o.x = cvt_pk_bf16(s[0 * 33] * g0[0], s[1 * 33] * g0[1]); o.y = cvt_pk_bf16(s[2 * 33] * g0[2], s[3 * 33] * g0[3]); o.z = cvt_pk_bf16(s[4 * 33] * g1[0], s[5 * 33] * g1[1]); o.w = cvt_pk_bf16(s[6 * 33] * g1[2], s[7 * 33] * g1[3]);
;         *(u32x4*)(dst + (size_t)n * K + k0 + 8 * c) = o; }
;     asm volatile("s_waitcnt lgkmcnt(0)" ::: "memory");
; }
; __global__ void __launch_bounds__(512) mega(Args a_byval) {
;     ...
;             it = xpose_all(a.in[27] + (size_t)lyr * D * D, nullptr, 2048, 2048, 2048, 2048, 0, (bf16_t*)(ws + (lyr ? WS_W_PG1 : WS_W_PG)), it, NGW, scr, lane, norm_ple_g + lyr * D);
.Lxpwid7_end:
	s_sub_i32 s59, s59, 0x2840
	s_cmpk_ge_i32 s59, 0x800
	s_cbranch_scc1 .Lxpq0d7_end
	s_load_dwordx2 s[60:61], s[92:93], 0xd8
	s_load_dwordx2 s[62:63], s[92:93], 0xe8
	s_load_dwordx2 s[64:65], s[92:93], 0x20
	v_mov_b32_e32 v5, 0x2000
	v_mul_u32_u24_e32 v5, v3, v5
	v_add_u32_e32 v5, v5, v4
	v_mov_b32_e32 v10, 0x1000
	v_mul_u32_u24_e32 v10, v8, v10
	v_lshl_add_u32 v12, v7, 4, v10
	v_add_u32_e32 v13, 0x8000, v12
	v_add_u32_e32 v14, 0x10000, v12
	v_add_u32_e32 v15, 0x18000, v12
	s_waitcnt lgkmcnt(0)
	s_add_u32 s62, s62, 0x7b00000
	s_addc_u32 s63, s63, 0
	s_add_u32 s64, s64, 0x0
	s_addc_u32 s65, s65, 0
	v_lshlrev_b32_e32 v16, 5, v7
	v_mov_b32_e32 v17, v0
	v_lshl_add_u64 v[16:17], s[64:65], 0, v[16:17]
	s_lshr_b32 s64, s59, 6
	s_and_b32 s65, s59, 63
	s_mul_i32 s66, s64, 0x80000
	s_lshl_b32 s67, s65, 7
	s_add_i32 s66, s66, s67
	s_add_u32 s66, s60, s66
	s_addc_u32 s67, s61, 0
	s_lshl_b32 s64, s64, 8
	s_mov_b32 s65, 0
	v_lshl_add_u64 v[18:19], s[64:65], 0, v[16:17]
	global_load_dwordx4 v[52:55], v[18:19], off
	global_load_dwordx4 v[56:59], v[18:19], off offset:16
	v_mov_b32_e32 v11, v5
	global_load_dword v20, v11, s[66:67] nt
	v_add_u32_e32 v11, 0x4000, v11
	global_load_dword v21, v11, s[66:67] nt
	v_add_u32_e32 v11, 0x4000, v11
	global_load_dword v22, v11, s[66:67] nt
	v_add_u32_e32 v11, 0x4000, v11
	global_load_dword v23, v11, s[66:67] nt
	v_add_u32_e32 v11, 0x4000, v11
	global_load_dword v24, v11, s[66:67] nt
	v_add_u32_e32 v11, 0x4000, v11
	global_load_dword v25, v11, s[66:67] nt
	v_add_u32_e32 v11, 0x4000, v11
	global_load_dword v26, v11, s[66:67] nt
	v_add_u32_e32 v11, 0x4000, v11
	global_load_dword v27, v11, s[66:67] nt
	v_add_u32_e32 v11, 0x4000, v11
	global_load_dword v28, v11, s[66:67] nt
	v_add_u32_e32 v11, 0x4000, v11
	global_load_dword v29, v11, s[66:67] nt
	v_add_u32_e32 v11, 0x4000, v11
	global_load_dword v30, v11, s[66:67] nt
	v_add_u32_e32 v11, 0x4000, v11
	global_load_dword v31, v11, s[66:67] nt
	v_add_u32_e32 v11, 0x4000, v11
	global_load_dword v32, v11, s[66:67] nt
	v_add_u32_e32 v11, 0x4000, v11
	global_load_dword v33, v11, s[66:67] nt
	v_add_u32_e32 v11, 0x4000, v11
	global_load_dword v34, v11, s[66:67] nt
	v_add_u32_e32 v11, 0x4000, v11
	global_load_dword v35, v11, s[66:67] nt
	v_add_u32_e32 v11, 0x4000, v11
	global_load_dword v36, v11, s[66:67] nt
	v_add_u32_e32 v11, 0x4000, v11
	global_load_dword v37, v11, s[66:67] nt
	v_add_u32_e32 v11, 0x4000, v11
	global_load_dword v38, v11, s[66:67] nt
	v_add_u32_e32 v11, 0x4000, v11
	global_load_dword v39, v11, s[66:67] nt
	v_add_u32_e32 v11, 0x4000, v11
	global_load_dword v40, v11, s[66:67] nt
	v_add_u32_e32 v11, 0x4000, v11
	global_load_dword v41, v11, s[66:67] nt
	v_add_u32_e32 v11, 0x4000, v11
	global_load_dword v42, v11, s[66:67] nt
	v_add_u32_e32 v11, 0x4000, v11
	global_load_dword v43, v11, s[66:67] nt
	v_add_u32_e32 v11, 0x4000, v11
	global_load_dword v44, v11, s[66:67] nt
	v_add_u32_e32 v11, 0x4000, v11
	global_load_dword v45, v11, s[66:67] nt
	v_add_u32_e32 v11, 0x4000, v11
	global_load_dword v46, v11, s[66:67] nt
	v_add_u32_e32 v11, 0x4000, v11
	global_load_dword v47, v11, s[66:67] nt
	v_add_u32_e32 v11, 0x4000, v11
	global_load_dword v48, v11, s[66:67] nt
	v_add_u32_e32 v11, 0x4000, v11
	global_load_dword v49, v11, s[66:67] nt
	v_add_u32_e32 v11, 0x4000, v11
	global_load_dword v50, v11, s[66:67] nt
	v_add_u32_e32 v11, 0x4000, v11
	global_load_dword v51, v11, s[66:67] nt
.Lxpq0d7_loop:
	s_add_i32 s32, s59, 0x80
	s_cmpk_lt_i32 s32, 0x800
	s_cbranch_scc0 .Lxpq0d7_dumB
	s_lshr_b32 s64, s32, 6
	s_and_b32 s65, s32, 63
	s_mul_i32 s66, s64, 0x80000
	s_lshl_b32 s67, s65, 7
	s_add_i32 s66, s66, s67
	s_add_u32 s66, s60, s66
	s_addc_u32 s67, s61, 0
	s_lshl_b32 s64, s64, 8
	s_mov_b32 s65, 0
	v_lshl_add_u64 v[18:19], s[64:65], 0, v[16:17]
	global_load_dwordx4 v[160:163], v[18:19], off
	global_load_dwordx4 v[164:167], v[18:19], off offset:16
	v_mov_b32_e32 v11, v5
	global_load_dword v108, v11, s[66:67] nt
	v_add_u32_e32 v11, 0x4000, v11
	global_load_dword v109, v11, s[66:67] nt
	v_add_u32_e32 v11, 0x4000, v11
	global_load_dword v110, v11, s[66:67] nt
	v_add_u32_e32 v11, 0x4000, v11
	global_load_dword v111, v11, s[66:67] nt
	v_add_u32_e32 v11, 0x4000, v11
	global_load_dword v112, v11, s[66:67] nt
	v_add_u32_e32 v11, 0x4000, v11
	global_load_dword v113, v11, s[66:67] nt
	v_add_u32_e32 v11, 0x4000, v11
	global_load_dword v114, v11, s[66:67] nt
	v_add_u32_e32 v11, 0x4000, v11
	global_load_dword v115, v11, s[66:67] nt
	v_add_u32_e32 v11, 0x4000, v11
	global_load_dword v116, v11, s[66:67] nt
	v_add_u32_e32 v11, 0x4000, v11
	global_load_dword v117, v11, s[66:67] nt
	v_add_u32_e32 v11, 0x4000, v11
	global_load_dword v118, v11, s[66:67] nt
	v_add_u32_e32 v11, 0x4000, v11
	global_load_dword v119, v11, s[66:67] nt
	v_add_u32_e32 v11, 0x4000, v11
	global_load_dword v120, v11, s[66:67] nt
	v_add_u32_e32 v11, 0x4000, v11
	global_load_dword v121, v11, s[66:67] nt
	v_add_u32_e32 v11, 0x4000, v11
	global_load_dword v122, v11, s[66:67] nt
	v_add_u32_e32 v11, 0x4000, v11
	global_load_dword v123, v11, s[66:67] nt
	v_add_u32_e32 v11, 0x4000, v11
	global_load_dword v124, v11, s[66:67] nt
	v_add_u32_e32 v11, 0x4000, v11
	global_load_dword v125, v11, s[66:67] nt
	v_add_u32_e32 v11, 0x4000, v11
	global_load_dword v126, v11, s[66:67] nt
	v_add_u32_e32 v11, 0x4000, v11
	global_load_dword v127, v11, s[66:67] nt
	v_add_u32_e32 v11, 0x4000, v11
	global_load_dword v128, v11, s[66:67] nt
	v_add_u32_e32 v11, 0x4000, v11
	global_load_dword v129, v11, s[66:67] nt
	v_add_u32_e32 v11, 0x4000, v11
	global_load_dword v130, v11, s[66:67] nt
	v_add_u32_e32 v11, 0x4000, v11
	global_load_dword v131, v11, s[66:67] nt
	v_add_u32_e32 v11, 0x4000, v11
	global_load_dword v132, v11, s[66:67] nt
	v_add_u32_e32 v11, 0x4000, v11
	global_load_dword v133, v11, s[66:67] nt
	v_add_u32_e32 v11, 0x4000, v11
	global_load_dword v134, v11, s[66:67] nt
	v_add_u32_e32 v11, 0x4000, v11
	global_load_dword v135, v11, s[66:67] nt
	v_add_u32_e32 v11, 0x4000, v11
	global_load_dword v136, v11, s[66:67] nt
	v_add_u32_e32 v11, 0x4000, v11
	global_load_dword v137, v11, s[66:67] nt
	v_add_u32_e32 v11, 0x4000, v11
	global_load_dword v138, v11, s[66:67] nt
	v_add_u32_e32 v11, 0x4000, v11
	global_load_dword v139, v11, s[66:67] nt
	s_branch .Lxpq0d7_procA

; #define LAS __attribute__((address_space(3)))
; __device__ __forceinline__ unsigned cvt_pk_bf16(float lo, float hi) { unsigned r; asm volatile("v_cvt_pk_bf16_f32 %0, %1, %2" : "=v"(r) : "v"(lo), "v"(hi)); return r; }
; __device__ __forceinline__ void xpose_item(const float* src, int ld, bf16_t* dst, int K, int k0, LAS float* scr, int lane, const float* gk) {
;     ...
;     const int c = lane & 7;
;     f32x4 g0 = (f32x4){1.f, 1.f, 1.f, 1.f}, g1 = g0;
;     if (gk) { g0 = *(const f32x4*)(gk + k0 + 8 * c); g1 = *(const f32x4*)(gk + k0 + 8 * c + 4); }
;     asm volatile("s_waitcnt lgkmcnt(0)" ::: "memory");
; #pragma unroll
;     for (int j = 0; j < 4; ++j) { const int n = (lane >> 3) + 8 * j; const LAS float* s = scr + (8 * c) * 33 + n;
;         u32x4 o; o.x = cvt_pk_bf16(s[0 * 33] * g0[0], s[1 * 33] * g0[1]); o.y = cvt_pk_bf16(s[2 * 33] * g0[2], s[3 * 33] * g0[3]); o.z = cvt_pk_bf16(s[4 * 33] * g1[0], s[5 * 33] * g1[1]); o.w = cvt_pk_bf16(s[6 * 33] * g1[2], s[7 * 33] * g1[3]);
;         *(u32x4*)(dst + (size_t)n * K + k0 + 8 * c) = o; }
; __global__ void __launch_bounds__(512) mega(Args a_byval) {
;     ...
;             it = xpose_all(a.in[27] + (size_t)lyr * D * D, nullptr, 2048, 2048, 2048, 2048, 0, (bf16_t*)(ws + (lyr ? WS_W_PG1 : WS_W_PG)), it, NGW, scr, lane, norm_ple_g + lyr * D);
.Lxpq0d7_procA:
	s_lshr_b32 s64, s59, 6
	s_and_b32 s65, s59, 63
	s_mul_i32 s68, s65, 0x20000
	s_lshl_b32 s64, s64, 7
	s_add_i32 s68, s68, s64
	s_add_u32 s64, s62, s68
	s_addc_u32 s65, s63, 0
	s_waitcnt vmcnt(63)
	ds_write_b32 v6, v20 offset:0
	s_waitcnt vmcnt(62)
	ds_write_b32 v6, v21 offset:264
	s_waitcnt vmcnt(61)
	ds_write_b32 v6, v22 offset:528
	s_waitcnt vmcnt(60)
	ds_write_b32 v6, v23 offset:792
	s_waitcnt vmcnt(59)
	ds_write_b32 v6, v24 offset:1056
	s_waitcnt vmcnt(58)
	ds_write_b32 v6, v25 offset:1320
	s_waitcnt vmcnt(57)
	ds_write_b32 v6, v26 offset:1584
	s_waitcnt vmcnt(56)
	ds_write_b32 v6, v27 offset:1848
	s_waitcnt vmcnt(55)
	ds_write_b32 v6, v28 offset:2112
	s_waitcnt vmcnt(54)
	ds_write_b32 v6, v29 offset:2376
	s_waitcnt vmcnt(53)
	ds_write_b32 v6, v30 offset:2640
	s_waitcnt vmcnt(52)
	ds_write_b32 v6, v31 offset:2904
	s_waitcnt vmcnt(51)
	ds_write_b32 v6, v32 offset:3168
	s_waitcnt vmcnt(50)
	ds_write_b32 v6, v33 offset:3432
	s_waitcnt vmcnt(49)
	ds_write_b32 v6, v34 offset:3696
	s_waitcnt vmcnt(48)
	ds_write_b32 v6, v35 offset:3960
	s_waitcnt vmcnt(47)
	ds_write_b32 v6, v36 offset:4224
	s_waitcnt vmcnt(46)
	ds_write_b32 v6, v37 offset:4488
	s_waitcnt vmcnt(45)
	ds_write_b32 v6, v38 offset:4752
	s_waitcnt vmcnt(44)
	ds_write_b32 v6, v39 offset:5016
	s_waitcnt vmcnt(43)
	ds_write_b32 v6, v40 offset:5280
	s_waitcnt vmcnt(42)
	ds_write_b32 v6, v41 offset:5544
	s_waitcnt vmcnt(41)
	ds_write_b32 v6, v42 offset:5808
	s_waitcnt vmcnt(40)
	ds_write_b32 v6, v43 offset:6072
	s_waitcnt vmcnt(39)
	ds_write_b32 v6, v44 offset:6336
	s_waitcnt vmcnt(38)
	ds_write_b32 v6, v45 offset:6600
	s_waitcnt vmcnt(37)
	ds_write_b32 v6, v46 offset:6864
	s_waitcnt vmcnt(36)
	ds_write_b32 v6, v47 offset:7128
	s_waitcnt vmcnt(35)
	ds_write_b32 v6, v48 offset:7392
	s_waitcnt vmcnt(34)
	ds_write_b32 v6, v49 offset:7656
	s_waitcnt vmcnt(33)
	ds_write_b32 v6, v50 offset:7920
	s_waitcnt vmcnt(32)
	ds_write_b32 v6, v51 offset:8184
	s_waitcnt lgkmcnt(0)
	ds_read2_b32 v[60:61], v9 offset0:0 offset1:33
	ds_read2_b32 v[62:63], v9 offset0:66 offset1:99
	ds_read2_b32 v[64:65], v9 offset0:132 offset1:165
	ds_read2_b32 v[66:67], v9 offset0:198 offset1:231
	ds_read2_b32 v[68:69], v9 offset0:8 offset1:41
	ds_read2_b32 v[70:71], v9 offset0:74 offset1:107
	ds_read2_b32 v[72:73], v9 offset0:140 offset1:173
	ds_read2_b32 v[74:75], v9 offset0:206 offset1:239
	ds_read2_b32 v[76:77], v9 offset0:16 offset1:49
	ds_read2_b32 v[78:79], v9 offset0:82 offset1:115
	ds_read2_b32 v[80:81], v9 offset0:148 offset1:181
	ds_read2_b32 v[82:83], v9 offset0:214 offset1:247
	ds_read2_b32 v[84:85], v9 offset0:24 offset1:57
	ds_read2_b32 v[86:87], v9 offset0:90 offset1:123
	ds_read2_b32 v[88:89], v9 offset0:156 offset1:189
	ds_read2_b32 v[90:91], v9 offset0:222 offset1:255
	s_waitcnt lgkmcnt(12)
	v_mul_f32_e32 v60, v60, v52
	v_mul_f32_e32 v61, v61, v53
	v_mul_f32_e32 v62, v62, v54
	v_mul_f32_e32 v63, v63, v55
	v_mul_f32_e32 v64, v64, v56
	v_mul_f32_e32 v65, v65, v57
	v_mul_f32_e32 v66, v66, v58
	v_mul_f32_e32 v67, v67, v59
	v_cvt_pk_bf16_f32 v92, v60, v61
	v_cvt_pk_bf16_f32 v93, v62, v63
	v_cvt_pk_bf16_f32 v94, v64, v65
	v_cvt_pk_bf16_f32 v95, v66, v67
	global_store_dwordx4 v12, v[92:95], s[64:65]
	s_waitcnt lgkmcnt(8)
	v_mul_f32_e32 v68, v68, v52
	v_mul_f32_e32 v69, v69, v53
	v_mul_f32_e32 v70, v70, v54
	v_mul_f32_e32 v71, v71, v55
	v_mul_f32_e32 v72, v72, v56
	v_mul_f32_e32 v73, v73, v57
	v_mul_f32_e32 v74, v74, v58
	v_mul_f32_e32 v75, v75, v59
	v_cvt_pk_bf16_f32 v96, v68, v69
	v_cvt_pk_bf16_f32 v97, v70, v71
	v_cvt_pk_bf16_f32 v98, v72, v73
	v_cvt_pk_bf16_f32 v99, v74, v75
	global_store_dwordx4 v13, v[96:99], s[64:65]
	s_waitcnt lgkmcnt(4)
	v_mul_f32_e32 v76, v76, v52
	v_mul_f32_e32 v77, v77, v53
	v_mul_f32_e32 v78, v78, v54
	v_mul_f32_e32 v79, v79, v55
	v_mul_f32_e32 v80, v80, v56
	v_mul_f32_e32 v81, v81, v57
	v_mul_f32_e32 v82, v82, v58
	v_mul_f32_e32 v83, v83, v59
	v_cvt_pk_bf16_f32 v100, v76, v77
	v_cvt_pk_bf16_f32 v101, v78, v79
	v_cvt_pk_bf16_f32 v102, v80, v81
	v_cvt_pk_bf16_f32 v103, v82, v83
	global_store_dwordx4 v14, v[100:103], s[64:65]
	s_waitcnt lgkmcnt(0)
	v_mul_f32_e32 v84, v84, v52
	v_mul_f32_e32 v85, v85, v53
	v_mul_f32_e32 v86, v86, v54
	v_mul_f32_e32 v87, v87, v55
	v_mul_f32_e32 v88, v88, v56
	v_mul_f32_e32 v89, v89, v57
	v_mul_f32_e32 v90, v90, v58
	v_mul_f32_e32 v91, v91, v59
	v_cvt_pk_bf16_f32 v104, v84, v85
	v_cvt_pk_bf16_f32 v105, v86, v87
	v_cvt_pk_bf16_f32 v106, v88, v89
	v_cvt_pk_bf16_f32 v107, v90, v91
	global_store_dwordx4 v15, v[104:107], s[64:65]
	s_cmpk_lt_i32 s32, 0x800
	s_cbranch_scc0 .Lxpq0d7_fin
; #define LAS __attribute__((address_space(3)))
; __device__ __forceinline__ void xpose_item(const float* src, int ld, bf16_t* dst, int K, int k0, LAS float* scr, int lane, const float* gk) {
;     if (src) {
; #pragma unroll 8
;         for (int i = 0; i < 32; ++i) { const int kk = 2 * i + (lane >> 5); scr[kk * 33 + (lane & 31)] = __builtin_nontemporal_load(src + (size_t)(k0 + kk) * ld + (lane & 31)); }
;     } else {
; #pragma unroll 8
;         for (int i = 0; i < 32; ++i) { const int kk = 2 * i + (lane >> 5); scr[kk * 33 + (lane & 31)] = 0.f; }
;     }
;     const int c = lane & 7;
;     f32x4 g0 = (f32x4){1.f, 1.f, 1.f, 1.f}, g1 = g0;
;     if (gk) { g0 = *(const f32x4*)(gk + k0 + 8 * c); g1 = *(const f32x4*)(gk + k0 + 8 * c + 4); }
; __global__ void __launch_bounds__(512) mega(Args a_byval) {
;     ...
;             it = xpose_all(a.in[27] + (size_t)lyr * D * D, nullptr, 2048, 2048, 2048, 2048, 0, (bf16_t*)(ws + (lyr ? WS_W_PG1 : WS_W_PG)), it, NGW, scr, lane, norm_ple_g + lyr * D);
	s_add_i32 s59, s32, 0x80
	s_cmpk_lt_i32 s59, 0x800
	s_cbranch_scc0 .Lxpq0d7_dumA
	s_lshr_b32 s64, s59, 6
	s_and_b32 s65, s59, 63
	s_mul_i32 s66, s64, 0x80000
	s_lshl_b32 s67, s65, 7
	s_add_i32 s66, s66, s67
	s_add_u32 s66, s60, s66
	s_addc_u32 s67, s61, 0
	s_lshl_b32 s64, s64, 8
	s_mov_b32 s65, 0
	v_lshl_add_u64 v[18:19], s[64:65], 0, v[16:17]
	global_load_dwordx4 v[52:55], v[18:19], off
	global_load_dwordx4 v[56:59], v[18:19], off offset:16
	v_mov_b32_e32 v11, v5
	global_load_dword v20, v11, s[66:67] nt
	v_add_u32_e32 v11, 0x4000, v11
	global_load_dword v21, v11, s[66:67] nt
	v_add_u32_e32 v11, 0x4000, v11
	global_load_dword v22, v11, s[66:67] nt
	v_add_u32_e32 v11, 0x4000, v11
	global_load_dword v23, v11, s[66:67] nt
	v_add_u32_e32 v11, 0x4000, v11
	global_load_dword v24, v11, s[66:67] nt
	v_add_u32_e32 v11, 0x4000, v11
	global_load_dword v25, v11, s[66:67] nt
	v_add_u32_e32 v11, 0x4000, v11
	global_load_dword v26, v11, s[66:67] nt
	v_add_u32_e32 v11, 0x4000, v11
	global_load_dword v27, v11, s[66:67] nt
	v_add_u32_e32 v11, 0x4000, v11
	global_load_dword v28, v11, s[66:67] nt
	v_add_u32_e32 v11, 0x4000, v11
	global_load_dword v29, v11, s[66:67] nt
	v_add_u32_e32 v11, 0x4000, v11
	global_load_dword v30, v11, s[66:67] nt
	v_add_u32_e32 v11, 0x4000, v11
	global_load_dword v31, v11, s[66:67] nt
	v_add_u32_e32 v11, 0x4000, v11
	global_load_dword v32, v11, s[66:67] nt
	v_add_u32_e32 v11, 0x4000, v11
	global_load_dword v33, v11, s[66:67] nt
	v_add_u32_e32 v11, 0x4000, v11
	global_load_dword v34, v11, s[66:67] nt
	v_add_u32_e32 v11, 0x4000, v11
	global_load_dword v35, v11, s[66:67] nt
	v_add_u32_e32 v11, 0x4000, v11
	global_load_dword v36, v11, s[66:67] nt
	v_add_u32_e32 v11, 0x4000, v11
	global_load_dword v37, v11, s[66:67] nt
	v_add_u32_e32 v11, 0x4000, v11
	global_load_dword v38, v11, s[66:67] nt
	v_add_u32_e32 v11, 0x4000, v11
	global_load_dword v39, v11, s[66:67] nt
	v_add_u32_e32 v11, 0x4000, v11
	global_load_dword v40, v11, s[66:67] nt
	v_add_u32_e32 v11, 0x4000, v11
	global_load_dword v41, v11, s[66:67] nt
	v_add_u32_e32 v11, 0x4000, v11
	global_load_dword v42, v11, s[66:67] nt
	v_add_u32_e32 v11, 0x4000, v11
	global_load_dword v43, v11, s[66:67] nt
	v_add_u32_e32 v11, 0x4000, v11
	global_load_dword v44, v11, s[66:67] nt
	v_add_u32_e32 v11, 0x4000, v11
	global_load_dword v45, v11, s[66:67] nt
	v_add_u32_e32 v11, 0x4000, v11
	global_load_dword v46, v11, s[66:67] nt
	v_add_u32_e32 v11, 0x4000, v11
	global_load_dword v47, v11, s[66:67] nt
	v_add_u32_e32 v11, 0x4000, v11
	global_load_dword v48, v11, s[66:67] nt
	v_add_u32_e32 v11, 0x4000, v11
	global_load_dword v49, v11, s[66:67] nt
	v_add_u32_e32 v11, 0x4000, v11
	global_load_dword v50, v11, s[66:67] nt
	v_add_u32_e32 v11, 0x4000, v11
	global_load_dword v51, v11, s[66:67] nt
	s_branch .Lxpq0d7_procB

; #define LAS __attribute__((address_space(3)))
; __device__ __forceinline__ void xpose_item(const float* src, int ld, bf16_t* dst, int K, int k0, LAS float* scr, int lane, const float* gk) {
;     if (src) {
; #pragma unroll 8
;         for (int i = 0; i < 32; ++i) { const int kk = 2 * i + (lane >> 5); scr[kk * 33 + (lane & 31)] = __builtin_nontemporal_load(src + (size_t)(k0 + kk) * ld + (lane & 31)); }
;     } else {
; #pragma unroll 8
;         for (int i = 0; i < 32; ++i) { const int kk = 2 * i + (lane >> 5); scr[kk * 33 + (lane & 31)] = 0.f; }
; __global__ void __launch_bounds__(512) mega(Args a_byval) {
;     ...
;             it = xpose_all(a.in[26] + (size_t)lyr * PLE * D, nullptr, 2048, 256, 2048, 2048, 0, (bf16_t*)(ws + (lyr ? WS_W_PP1 : WS_W_PP)), it, NGW, scr, lane);
.Lxpr0d7_loop:
	s_add_i32 s32, s59, 0x80
	s_cmpk_lt_i32 s32, 0x100
	s_cbranch_scc0 .Lxpr0d7_dumB
	s_lshr_b32 s64, s32, 6
	s_and_b32 s65, s32, 63
	s_mul_i32 s66, s64, 0x80000
	s_lshl_b32 s67, s65, 7
	s_add_i32 s66, s66, s67
	s_add_u32 s66, s60, s66
	s_addc_u32 s67, s61, 0
	v_mov_b32_e32 v11, v5
	global_load_dword v108, v11, s[66:67] nt
	v_add_u32_e32 v11, 0x4000, v11
	global_load_dword v109, v11, s[66:67] nt
	v_add_u32_e32 v11, 0x4000, v11
	global_load_dword v110, v11, s[66:67] nt
	v_add_u32_e32 v11, 0x4000, v11
	global_load_dword v111, v11, s[66:67] nt
	v_add_u32_e32 v11, 0x4000, v11
	global_load_dword v112, v11, s[66:67] nt
	v_add_u32_e32 v11, 0x4000, v11
	global_load_dword v113, v11, s[66:67] nt
	v_add_u32_e32 v11, 0x4000, v11
	global_load_dword v114, v11, s[66:67] nt
	v_add_u32_e32 v11, 0x4000, v11
	global_load_dword v115, v11, s[66:67] nt
	v_add_u32_e32 v11, 0x4000, v11
	global_load_dword v116, v11, s[66:67] nt
	v_add_u32_e32 v11, 0x4000, v11
	global_load_dword v117, v11, s[66:67] nt
	v_add_u32_e32 v11, 0x4000, v11
	global_load_dword v118, v11, s[66:67] nt
	v_add_u32_e32 v11, 0x4000, v11
	global_load_dword v119, v11, s[66:67] nt
	v_add_u32_e32 v11, 0x4000, v11
	global_load_dword v120, v11, s[66:67] nt
	v_add_u32_e32 v11, 0x4000, v11
	global_load_dword v121, v11, s[66:67] nt
	v_add_u32_e32 v11, 0x4000, v11
	global_load_dword v122, v11, s[66:67] nt
	v_add_u32_e32 v11, 0x4000, v11
	global_load_dword v123, v11, s[66:67] nt
	v_add_u32_e32 v11, 0x4000, v11
	global_load_dword v124, v11, s[66:67] nt
	v_add_u32_e32 v11, 0x4000, v11
	global_load_dword v125, v11, s[66:67] nt
	v_add_u32_e32 v11, 0x4000, v11
	global_load_dword v126, v11, s[66:67] nt
	v_add_u32_e32 v11, 0x4000, v11
	global_load_dword v127, v11, s[66:67] nt
	v_add_u32_e32 v11, 0x4000, v11
	global_load_dword v128, v11, s[66:67] nt
	v_add_u32_e32 v11, 0x4000, v11
	global_load_dword v129, v11, s[66:67] nt
	v_add_u32_e32 v11, 0x4000, v11
	global_load_dword v130, v11, s[66:67] nt
	v_add_u32_e32 v11, 0x4000, v11
	global_load_dword v131, v11, s[66:67] nt
	v_add_u32_e32 v11, 0x4000, v11
	global_load_dword v132, v11, s[66:67] nt
	v_add_u32_e32 v11, 0x4000, v11
	global_load_dword v133, v11, s[66:67] nt
	v_add_u32_e32 v11, 0x4000, v11
	global_load_dword v134, v11, s[66:67] nt
	v_add_u32_e32 v11, 0x4000, v11
	global_load_dword v135, v11, s[66:67] nt
	v_add_u32_e32 v11, 0x4000, v11
	global_load_dword v136, v11, s[66:67] nt
	v_add_u32_e32 v11, 0x4000, v11
	global_load_dword v137, v11, s[66:67] nt
	v_add_u32_e32 v11, 0x4000, v11
	global_load_dword v138, v11, s[66:67] nt
	v_add_u32_e32 v11, 0x4000, v11
	global_load_dword v139, v11, s[66:67] nt
	s_branch .Lxpr0d7_procA

; #define LAS __attribute__((address_space(3)))
; __device__ __forceinline__ unsigned cvt_pk_bf16(float lo, float hi) { unsigned r; asm volatile("v_cvt_pk_bf16_f32 %0, %1, %2" : "=v"(r) : "v"(lo), "v"(hi)); return r; }
; __device__ __forceinline__ void xpose_item(const float* src, int ld, bf16_t* dst, int K, int k0, LAS float* scr, int lane, const float* gk) {
;     ...
;     const int c = lane & 7;
;     f32x4 g0 = (f32x4){1.f, 1.f, 1.f, 1.f}, g1 = g0;
;     if (gk) { g0 = *(const f32x4*)(gk + k0 + 8 * c); g1 = *(const f32x4*)(gk + k0 + 8 * c + 4); }
;     asm volatile("s_waitcnt lgkmcnt(0)" ::: "memory");
; #pragma unroll
;     for (int j = 0; j < 4; ++j) { const int n = (lane >> 3) + 8 * j; const LAS float* s = scr + (8 * c) * 33 + n;
;         u32x4 o; o.x = cvt_pk_bf16(s[0 * 33] * g0[0], s[1 * 33] * g0[1]); o.y = cvt_pk_bf16(s[2 * 33] * g0[2], s[3 * 33] * g0[3]); o.z = cvt_pk_bf16(s[4 * 33] * g1[0], s[5 * 33] * g1[1]); o.w = cvt_pk_bf16(s[6 * 33] * g1[2], s[7 * 33] * g1[3]);
;         *(u32x4*)(dst + (size_t)n * K + k0 + 8 * c) = o; }
; __global__ void __launch_bounds__(512) mega(Args a_byval) {
;     ...
;             it = xpose_all(a.in[26] + (size_t)lyr * PLE * D, nullptr, 2048, 256, 2048, 2048, 0, (bf16_t*)(ws + (lyr ? WS_W_PP1 : WS_W_PP)), it, NGW, scr, lane);
.Lxpr0d7_procA:
	s_lshr_b32 s64, s59, 6
	s_and_b32 s65, s59, 63
	s_mul_i32 s68, s65, 0x4000
	s_lshl_b32 s64, s64, 7
	s_add_i32 s68, s68, s64
	s_add_u32 s64, s62, s68
	s_addc_u32 s65, s63, 0
	s_waitcnt vmcnt(63)
	ds_write_b32 v6, v20 offset:0
	s_waitcnt vmcnt(62)
	ds_write_b32 v6, v21 offset:264
	s_waitcnt vmcnt(61)
	ds_write_b32 v6, v22 offset:528
	s_waitcnt vmcnt(60)
	ds_write_b32 v6, v23 offset:792
	s_waitcnt vmcnt(59)
	ds_write_b32 v6, v24 offset:1056
	s_waitcnt vmcnt(58)
	ds_write_b32 v6, v25 offset:1320
	s_waitcnt vmcnt(57)
	ds_write_b32 v6, v26 offset:1584
	s_waitcnt vmcnt(56)
	ds_write_b32 v6, v27 offset:1848
	s_waitcnt vmcnt(55)
	ds_write_b32 v6, v28 offset:2112
	s_waitcnt vmcnt(54)
	ds_write_b32 v6, v29 offset:2376
	s_waitcnt vmcnt(53)
	ds_write_b32 v6, v30 offset:2640
	s_waitcnt vmcnt(52)
	ds_write_b32 v6, v31 offset:2904
	s_waitcnt vmcnt(51)
	ds_write_b32 v6, v32 offset:3168
	s_waitcnt vmcnt(50)
	ds_write_b32 v6, v33 offset:3432
	s_waitcnt vmcnt(49)
	ds_write_b32 v6, v34 offset:3696
	s_waitcnt vmcnt(48)
	ds_write_b32 v6, v35 offset:3960
	s_waitcnt vmcnt(47)
	ds_write_b32 v6, v36 offset:4224
	s_waitcnt vmcnt(46)
	ds_write_b32 v6, v37 offset:4488
	s_waitcnt vmcnt(45)
	ds_write_b32 v6, v38 offset:4752
	s_waitcnt vmcnt(44)
	ds_write_b32 v6, v39 offset:5016
	s_waitcnt vmcnt(43)
	ds_write_b32 v6, v40 offset:5280
	s_waitcnt vmcnt(42)
	ds_write_b32 v6, v41 offset:5544
	s_waitcnt vmcnt(41)
	ds_write_b32 v6, v42 offset:5808
	s_waitcnt vmcnt(40)
	ds_write_b32 v6, v43 offset:6072
	s_waitcnt vmcnt(39)
	ds_write_b32 v6, v44 offset:6336
	s_waitcnt vmcnt(38)
	ds_write_b32 v6, v45 offset:6600
	s_waitcnt vmcnt(37)
	ds_write_b32 v6, v46 offset:6864
	s_waitcnt vmcnt(36)
	ds_write_b32 v6, v47 offset:7128
	s_waitcnt vmcnt(35)
	ds_write_b32 v6, v48 offset:7392
	s_waitcnt vmcnt(34)
	ds_write_b32 v6, v49 offset:7656
	s_waitcnt vmcnt(33)
	ds_write_b32 v6, v50 offset:7920
	s_waitcnt vmcnt(32)
	ds_write_b32 v6, v51 offset:8184
	s_waitcnt lgkmcnt(0)
	ds_read2_b32 v[60:61], v9 offset0:0 offset1:33
	ds_read2_b32 v[62:63], v9 offset0:66 offset1:99
	ds_read2_b32 v[64:65], v9 offset0:132 offset1:165
	ds_read2_b32 v[66:67], v9 offset0:198 offset1:231
	ds_read2_b32 v[68:69], v9 offset0:8 offset1:41
	ds_read2_b32 v[70:71], v9 offset0:74 offset1:107
	ds_read2_b32 v[72:73], v9 offset0:140 offset1:173
	ds_read2_b32 v[74:75], v9 offset0:206 offset1:239
	ds_read2_b32 v[76:77], v9 offset0:16 offset1:49
	ds_read2_b32 v[78:79], v9 offset0:82 offset1:115
	ds_read2_b32 v[80:81], v9 offset0:148 offset1:181
	ds_read2_b32 v[82:83], v9 offset0:214 offset1:247
	ds_read2_b32 v[84:85], v9 offset0:24 offset1:57
	ds_read2_b32 v[86:87], v9 offset0:90 offset1:123
	ds_read2_b32 v[88:89], v9 offset0:156 offset1:189
	ds_read2_b32 v[90:91], v9 offset0:222 offset1:255
	s_waitcnt lgkmcnt(12)
	v_cvt_pk_bf16_f32 v92, v60, v61
	v_cvt_pk_bf16_f32 v93, v62, v63
	v_cvt_pk_bf16_f32 v94, v64, v65
	v_cvt_pk_bf16_f32 v95, v66, v67
	global_store_dwordx4 v12, v[92:95], s[64:65]
	s_waitcnt lgkmcnt(8)
	v_cvt_pk_bf16_f32 v96, v68, v69
	v_cvt_pk_bf16_f32 v97, v70, v71
	v_cvt_pk_bf16_f32 v98, v72, v73
	v_cvt_pk_bf16_f32 v99, v74, v75
	global_store_dwordx4 v13, v[96:99], s[64:65]
	s_waitcnt lgkmcnt(4)
	v_cvt_pk_bf16_f32 v100, v76, v77
	v_cvt_pk_bf16_f32 v101, v78, v79
	v_cvt_pk_bf16_f32 v102, v80, v81
	v_cvt_pk_bf16_f32 v103, v82, v83
	global_store_dwordx4 v14, v[100:103], s[64:65]
	s_waitcnt lgkmcnt(0)
	v_cvt_pk_bf16_f32 v104, v84, v85
	v_cvt_pk_bf16_f32 v105, v86, v87
	v_cvt_pk_bf16_f32 v106, v88, v89
	v_cvt_pk_bf16_f32 v107, v90, v91
	global_store_dwordx4 v15, v[104:107], s[64:65]
	s_cmpk_lt_i32 s32, 0x100
	s_cbranch_scc0 .Lxpr0d7_fin
	s_add_i32 s59, s32, 0x80
	s_cmpk_lt_i32 s59, 0x100
	s_cbranch_scc0 .Lxpr0d7_dumA
	s_lshr_b32 s64, s59, 6
	s_and_b32 s65, s59, 63
	s_mul_i32 s66, s64, 0x80000
	s_lshl_b32 s67, s65, 7
	s_add_i32 s66, s66, s67
	s_add_u32 s66, s60, s66
	s_addc_u32 s67, s61, 0
	v_mov_b32_e32 v11, v5
	global_load_dword v20, v11, s[66:67] nt
	v_add_u32_e32 v11, 0x4000, v11
	global_load_dword v21, v11, s[66:67] nt
	v_add_u32_e32 v11, 0x4000, v11
	global_load_dword v22, v11, s[66:67] nt
	v_add_u32_e32 v11, 0x4000, v11
	global_load_dword v23, v11, s[66:67] nt
	v_add_u32_e32 v11, 0x4000, v11
	global_load_dword v24, v11, s[66:67] nt
	v_add_u32_e32 v11, 0x4000, v11
	global_load_dword v25, v11, s[66:67] nt
	v_add_u32_e32 v11, 0x4000, v11
	global_load_dword v26, v11, s[66:67] nt
	v_add_u32_e32 v11, 0x4000, v11
	global_load_dword v27, v11, s[66:67] nt
	v_add_u32_e32 v11, 0x4000, v11
	global_load_dword v28, v11, s[66:67] nt
	v_add_u32_e32 v11, 0x4000, v11
	global_load_dword v29, v11, s[66:67] nt
	v_add_u32_e32 v11, 0x4000, v11
	global_load_dword v30, v11, s[66:67] nt
	v_add_u32_e32 v11, 0x4000, v11
	global_load_dword v31, v11, s[66:67] nt
	v_add_u32_e32 v11, 0x4000, v11
	global_load_dword v32, v11, s[66:67] nt
	v_add_u32_e32 v11, 0x4000, v11
	global_load_dword v33, v11, s[66:67] nt
	v_add_u32_e32 v11, 0x4000, v11
	global_load_dword v34, v11, s[66:67] nt
	v_add_u32_e32 v11, 0x4000, v11
	global_load_dword v35, v11, s[66:67] nt
	v_add_u32_e32 v11, 0x4000, v11
	global_load_dword v36, v11, s[66:67] nt
	v_add_u32_e32 v11, 0x4000, v11
	global_load_dword v37, v11, s[66:67] nt
	v_add_u32_e32 v11, 0x4000, v11
	global_load_dword v38, v11, s[66:67] nt
	v_add_u32_e32 v11, 0x4000, v11
	global_load_dword v39, v11, s[66:67] nt
	v_add_u32_e32 v11, 0x4000, v11
	global_load_dword v40, v11, s[66:67] nt
	v_add_u32_e32 v11, 0x4000, v11
	global_load_dword v41, v11, s[66:67] nt
	v_add_u32_e32 v11, 0x4000, v11
	global_load_dword v42, v11, s[66:67] nt
	v_add_u32_e32 v11, 0x4000, v11
	global_load_dword v43, v11, s[66:67] nt
	v_add_u32_e32 v11, 0x4000, v11
	global_load_dword v44, v11, s[66:67] nt
	v_add_u32_e32 v11, 0x4000, v11
	global_load_dword v45, v11, s[66:67] nt
	v_add_u32_e32 v11, 0x4000, v11
	global_load_dword v46, v11, s[66:67] nt
	v_add_u32_e32 v11, 0x4000, v11
	global_load_dword v47, v11, s[66:67] nt
	v_add_u32_e32 v11, 0x4000, v11
	global_load_dword v48, v11, s[66:67] nt
	v_add_u32_e32 v11, 0x4000, v11
	global_load_dword v49, v11, s[66:67] nt
	v_add_u32_e32 v11, 0x4000, v11
	global_load_dword v50, v11, s[66:67] nt
	v_add_u32_e32 v11, 0x4000, v11
	global_load_dword v51, v11, s[66:67] nt
	s_branch .Lxpr0d7_procB

; #define LAS __attribute__((address_space(3)))
; __device__ __forceinline__ void xpose_item(const float* src, int ld, bf16_t* dst, int K, int k0, LAS float* scr, int lane, const float* gk) {
;     if (src) {
; #pragma unroll 8
;         for (int i = 0; i < 32; ++i) { const int kk = 2 * i + (lane >> 5); scr[kk * 33 + (lane & 31)] = __builtin_nontemporal_load(src + (size_t)(k0 + kk) * ld + (lane & 31)); }
;     } else {
; #pragma unroll 8
;         for (int i = 0; i < 32; ++i) { const int kk = 2 * i + (lane >> 5); scr[kk * 33 + (lane & 31)] = 0.f; }
;     }
;     const int c = lane & 7;
;     f32x4 g0 = (f32x4){1.f, 1.f, 1.f, 1.f}, g1 = g0;
;     if (gk) { g0 = *(const f32x4*)(gk + k0 + 8 * c); g1 = *(const f32x4*)(gk + k0 + 8 * c + 4); }
; __global__ void __launch_bounds__(512) mega(Args a_byval) {
;     ...
;                 it = xpose_all(a.in[22], nullptr, 2048, 4096, 2048, 2048, 0, (bf16_t*)(ws + WS_WB_OUT), it, NGW, scr, lane);
.Lxpr0d7_end:
	s_sub_i32 s59, s59, 0x100
	s_movk_i32 s33, 0x84
.Lxcd7_done:
	s_cmp_lg_u32 s76, 7
	s_cbranch_scc1 .Lxct7_done
	v_readlane_b32 s59, v255, 5
	s_cmpk_lg_i32 s59, 0x100
	s_cbranch_scc1 .Lxct7_done
	s_cmpk_lt_i32 s94, 0xd0
	s_cbranch_scc1 .Lxct7_done
	s_cmpk_gt_i32 s94, 0xef
	s_cbranch_scc1 .Lxct7_done
	s_sub_i32 s59, s94, 0xd0
	s_lshl_b32 s59, s59, 3
	s_add_i32 s59, s59, s95
	s_mul_i32 s64, s95, 0x2100
	v_and_b32_e32 v2, 31, v200
	v_lshrrev_b32_e32 v3, 5, v200
	v_lshlrev_b32_e32 v4, 2, v2
	v_mul_u32_u24_e32 v6, 0x84, v3
	v_add3_u32 v6, v6, v4, s64
	v_and_b32_e32 v7, 7, v200
	v_lshrrev_b32_e32 v8, 3, v200
	v_mul_u32_u24_e32 v9, 0x420, v7
	v_lshl_add_u32 v9, v8, 2, v9
	v_add_u32_e32 v9, s64, v9
	s_cmpk_ge_i32 s59, 0x1000
	s_cbranch_scc1 .Lxpwot7_end
	s_load_dwordx2 s[60:61], s[92:93], 0xb0
	s_load_dwordx2 s[62:63], s[92:93], 0xe8
	v_mov_b32_e32 v5, 0x2000
	v_mul_u32_u24_e32 v5, v3, v5
	v_add_u32_e32 v5, v5, v4
	v_mov_b32_e32 v10, 0x2000
	v_mul_u32_u24_e32 v10, v8, v10
	v_lshl_add_u32 v12, v7, 4, v10
	v_add_u32_e32 v13, 0x10000, v12
	v_add_u32_e32 v14, 0x20000, v12
	v_add_u32_e32 v15, 0x30000, v12
	s_waitcnt lgkmcnt(0)
	s_add_u32 s62, s62, 0xad00000
	s_addc_u32 s63, s63, 0
	s_lshr_b32 s64, s59, 6
	s_and_b32 s65, s59, 63
	s_mul_i32 s66, s64, 0x80000
	s_lshl_b32 s67, s65, 7
	s_add_i32 s66, s66, s67
	s_add_u32 s66, s60, s66
	s_addc_u32 s67, s61, 0
	v_mov_b32_e32 v11, v5
	global_load_dword v20, v11, s[66:67] nt
	v_add_u32_e32 v11, 0x4000, v11
	global_load_dword v21, v11, s[66:67] nt
	v_add_u32_e32 v11, 0x4000, v11
	global_load_dword v22, v11, s[66:67] nt
	v_add_u32_e32 v11, 0x4000, v11
	global_load_dword v23, v11, s[66:67] nt
	v_add_u32_e32 v11, 0x4000, v11
	global_load_dword v24, v11, s[66:67] nt
	v_add_u32_e32 v11, 0x4000, v11
	global_load_dword v25, v11, s[66:67] nt
	v_add_u32_e32 v11, 0x4000, v11
	global_load_dword v26, v11, s[66:67] nt
	v_add_u32_e32 v11, 0x4000, v11
	global_load_dword v27, v11, s[66:67] nt
	v_add_u32_e32 v11, 0x4000, v11
	global_load_dword v28, v11, s[66:67] nt
	v_add_u32_e32 v11, 0x4000, v11
	global_load_dword v29, v11, s[66:67] nt
	v_add_u32_e32 v11, 0x4000, v11
	global_load_dword v30, v11, s[66:67] nt
	v_add_u32_e32 v11, 0x4000, v11
	global_load_dword v31, v11, s[66:67] nt
	v_add_u32_e32 v11, 0x4000, v11
	global_load_dword v32, v11, s[66:67] nt
	v_add_u32_e32 v11, 0x4000, v11
	global_load_dword v33, v11, s[66:67] nt
	v_add_u32_e32 v11, 0x4000, v11
	global_load_dword v34, v11, s[66:67] nt
	v_add_u32_e32 v11, 0x4000, v11
	global_load_dword v35, v11, s[66:67] nt
	v_add_u32_e32 v11, 0x4000, v11
	global_load_dword v36, v11, s[66:67] nt
	v_add_u32_e32 v11, 0x4000, v11
	global_load_dword v37, v11, s[66:67] nt
	v_add_u32_e32 v11, 0x4000, v11
	global_load_dword v38, v11, s[66:67] nt
	v_add_u32_e32 v11, 0x4000, v11
	global_load_dword v39, v11, s[66:67] nt
	v_add_u32_e32 v11, 0x4000, v11
	global_load_dword v40, v11, s[66:67] nt
	v_add_u32_e32 v11, 0x4000, v11
	global_load_dword v41, v11, s[66:67] nt
	v_add_u32_e32 v11, 0x4000, v11
	global_load_dword v42, v11, s[66:67] nt
	v_add_u32_e32 v11, 0x4000, v11
	global_load_dword v43, v11, s[66:67] nt
	v_add_u32_e32 v11, 0x4000, v11
	global_load_dword v44, v11, s[66:67] nt
	v_add_u32_e32 v11, 0x4000, v11
	global_load_dword v45, v11, s[66:67] nt
	v_add_u32_e32 v11, 0x4000, v11
	global_load_dword v46, v11, s[66:67] nt
	v_add_u32_e32 v11, 0x4000, v11
	global_load_dword v47, v11, s[66:67] nt
	v_add_u32_e32 v11, 0x4000, v11
	global_load_dword v48, v11, s[66:67] nt
	v_add_u32_e32 v11, 0x4000, v11
	global_load_dword v49, v11, s[66:67] nt
	v_add_u32_e32 v11, 0x4000, v11
	global_load_dword v50, v11, s[66:67] nt
	v_add_u32_e32 v11, 0x4000, v11
	global_load_dword v51, v11, s[66:67] nt

; __global__ void __launch_bounds__(512) mega(Args a_byval) {
;     ...
;             it = xpose_all(a.in[25] + (size_t)lyr * D * DFF, nullptr, 2048, DFF, 2048, 2048, 0, (bf16_t*)(ws + (lyr ? WS_W_D : WS_W_D0)), it, NGW, scr, lane);
;             it = xpose_all(a.in[27] + (size_t)lyr * D * D, nullptr, 2048, 2048, 2048, 2048, 0, (bf16_t*)(ws + (lyr ? WS_W_PG1 : WS_W_PG)), it, NGW, scr, lane, norm_ple_g + lyr * D);
;             it = xpose_all(a.in[26] + (size_t)lyr * PLE * D, nullptr, 2048, 256, 2048, 2048, 0, (bf16_t*)(ws + (lyr ? WS_W_PP1 : WS_W_PP)), it, NGW, scr, lane);
.Lxpf0p3e_end:
	s_sub_i32 s59, s59, 0x1600
	s_movk_i32 s33, 0x84
	s_waitcnt lgkmcnt(0)
	s_barrier

; __global__ void __launch_bounds__(512) mega(Args a_byval) {
;     ...
;             it = xpose_all(a.in[25] + (size_t)lyr * D * DFF, nullptr, 2048, DFF, 2048, 2048, 0, (bf16_t*)(ws + (lyr ? WS_W_D : WS_W_D0)), it, NGW, scr, lane);
;             it = xpose_all(a.in[27] + (size_t)lyr * D * D, nullptr, 2048, 2048, 2048, 2048, 0, (bf16_t*)(ws + (lyr ? WS_W_PG1 : WS_W_PG)), it, NGW, scr, lane, norm_ple_g + lyr * D);
;             it = xpose_all(a.in[26] + (size_t)lyr * PLE * D, nullptr, 2048, 256, 2048, 2048, 0, (bf16_t*)(ws + (lyr ? WS_W_PP1 : WS_W_PP)), it, NGW, scr, lane);
.Lxpf0p3x_end:
	s_sub_i32 s59, s59, 0x1600
	s_movk_i32 s33, 0x84
.Lsgp3x_done:
	s_load_dwordx2 s[38:39], s[92:93], 0xe8
	s_mov_b32 s23, 0x10c03000
